# phase-0 convT: each call's surplus tiles go to a rotating set of workgroups instead of always the lowest-numbered ones
# speedup vs baseline: 1.0475x; 1.0060x over previous
.LBB0_1026:
	v_mov_b32_e32 v4, v196
	v_readlane_b32 vcc_hi, v255, 44
	s_sub_i32 s0, s2, vcc_hi
	s_cmp_lt_i32 s0, 0
	s_cselect_b32 vcc_lo, s34, 0
	s_add_i32 s0, s0, vcc_lo
	s_add_i32 vcc_hi, vcc_hi, 160
	s_cmp_ge_u32 vcc_hi, s34
	s_cselect_b32 vcc_lo, s34, 0
	s_sub_i32 vcc_hi, vcc_hi, vcc_lo
	s_nop 0
	v_writelane_b32 v255, vcc_hi, 44
	v_mov_b32_e32 v0, v196
	s_lshl_b32 s0, s0, 1
	v_readfirstlane_b32 s1, v0
	s_ashr_i32 s1, s1, 8
	v_mov_b32_e32 v0, v196
	s_add_i32 s1, s1, s0
	s_nop 0
	v_readfirstlane_b32 s0, v0
	s_ashr_i32 s0, s0, 8
	s_sub_i32 s22, s1, s0
	s_cmpk_gt_i32 s22, 0x33f
	s_cbranch_scc1 .LBB0_1031
	v_readlane_b32 s4, v253, 14
	s_mul_i32 s0, s40, 0x680000
	v_readlane_b32 s6, v253, 16
	v_readlane_b32 s5, v253, 15
	v_readlane_b32 s7, v253, 17
	v_readlane_b32 s8, v253, 18
	v_readlane_b32 s9, v253, 19
	v_readlane_b32 s10, v253, 20
	v_readlane_b32 s11, v253, 21
	v_readlane_b32 s12, v253, 22
	v_readlane_b32 s13, v253, 23
	v_readlane_b32 s14, v253, 24
	v_readlane_b32 s15, v253, 25
	v_readlane_b32 s16, v253, 26
	v_readlane_b32 s17, v253, 27
	v_readlane_b32 s18, v253, 28
	v_readlane_b32 s19, v253, 29
	s_add_u32 s0, s6, s0
	s_addc_u32 s1, s7, 0
	v_readlane_b32 s4, v254, 59
	s_mul_i32 s20, s40, 0xd00000
	v_readlane_b32 s8, v254, 63
	v_mov_b32_e32 v0, v196
	v_readlane_b32 s9, v255, 0
	s_add_u32 s20, s8, s20
	s_addc_u32 s21, s9, 0
	v_readfirstlane_b32 s23, v0
	s_ashr_i32 s23, s23, 8
	s_add_i32 s23, s23, s22
	s_min_i32 s23, s23, 0x33f
	s_ashr_i32 s26, s23, 31
	s_lshr_b32 s26, s26, 28
	s_add_i32 s26, s23, s26
	s_and_b32 s27, s26, 0x3fff0
	v_bfe_u32 v6, v4, 6, 2
	s_sub_i32 s23, s23, s27
	v_lshl_or_b32 v5, s23, 6, v6
	s_lshl_b32 s23, s26, 2
	s_and_b32 s26, s23, 0xffffffc0
	s_ashr_i32 s27, s26, 31
	s_lshl_b64 s[26:27], s[26:27], 2
	s_add_u32 s26, s20, s26
	v_lshlrev_b32_e32 v0, 2, v4
	s_addc_u32 s27, s21, s27
	v_and_b32_e32 v0, 0xfc, v0
	s_waitcnt vmcnt(1)
	v_mul_lo_u32 v8, v5, s50
	v_lshl_add_u64 v[2:3], s[26:27], 0, v[0:1]
	v_ashrrev_i32_e32 v9, 31, v8
	v_lshl_add_u64 v[2:3], v[8:9], 2, v[2:3]
	v_add_co_u32_e32 v8, vcc, s48, v2
	s_mov_b32 s4, 0x27000
	s_nop 0
	v_addc_co_u32_e32 v9, vcc, 0, v3, vcc
	v_add_co_u32_e32 v10, vcc, s55, v2
	s_mov_b32 s23, 0xa9000
	s_nop 0
	v_addc_co_u32_e32 v11, vcc, 0, v3, vcc
	v_add_co_u32_e32 v12, vcc, s4, v2
	s_mov_b32 s4, 0x34000
	s_nop 0
	v_addc_co_u32_e32 v13, vcc, 0, v3, vcc
	v_add_co_u32_e32 v14, vcc, s4, v2
	s_mov_b32 s4, 0x41000
	s_nop 0
	v_addc_co_u32_e32 v15, vcc, 0, v3, vcc
	s_waitcnt vmcnt(0)
	v_add_co_u32_e32 v16, vcc, s4, v2
	s_mov_b32 s4, 0x5b000
	s_nop 0
	v_addc_co_u32_e32 v17, vcc, 0, v3, vcc
	v_add_co_u32_e32 v20, vcc, s53, v2
	v_mov_b32_e32 v5, v1
	s_nop 0
	v_addc_co_u32_e32 v21, vcc, 0, v3, vcc
	v_add_co_u32_e32 v22, vcc, s4, v2
	s_mov_b32 s4, 0x68000
	s_waitcnt lgkmcnt(4)
	v_addc_co_u32_e32 v23, vcc, 0, v3, vcc
	global_load_dword v7, v[2:3], off nt
	s_nop 0
	global_load_dword v9, v[8:9], off nt
	s_nop 0
	global_load_dword v10, v[10:11], off nt
	s_nop 0
	global_load_dword v11, v[12:13], off nt
	s_nop 0
	global_load_dword v12, v[14:15], off nt
	s_nop 0
	global_load_dword v14, v[16:17], off nt
	s_nop 0
	global_load_dword v16, v[20:21], off nt
	global_load_dword v17, v[22:23], off nt
	v_add_co_u32_e32 v20, vcc, s4, v2
	s_mov_b32 s4, 0x75000
	s_nop 0
	v_addc_co_u32_e32 v21, vcc, 0, v3, vcc
	v_add_co_u32_e32 v22, vcc, s4, v2
	s_mov_b32 s4, 0x82000
	s_nop 0
	v_addc_co_u32_e32 v23, vcc, 0, v3, vcc
	v_add_co_u32_e32 v24, vcc, s4, v2
	s_mov_b32 s4, 0x8f000
	s_nop 0
	v_addc_co_u32_e32 v25, vcc, 0, v3, vcc
	v_add_co_u32_e32 v26, vcc, s4, v2
	s_mov_b32 s4, 0x9c000
	s_nop 0
	v_addc_co_u32_e32 v27, vcc, 0, v3, vcc
	v_add_co_u32_e32 v28, vcc, s4, v2
	v_bfe_u32 v8, v4, 3, 5
	s_nop 0
	v_addc_co_u32_e32 v29, vcc, 0, v3, vcc
	v_add_co_u32_e32 v30, vcc, s23, v2
	s_mov_b32 s23, 0xb6000
	s_nop 0
	v_addc_co_u32_e32 v31, vcc, 0, v3, vcc
	s_waitcnt lgkmcnt(0)
	v_add_co_u32_e32 v32, vcc, s23, v2
	s_mov_b32 s23, 0xc3000
	s_nop 0
	v_addc_co_u32_e32 v33, vcc, 0, v3, vcc
	v_add_co_u32_e32 v2, vcc, s23, v2
	v_lshlrev_b32_e32 v4, 3, v4
	s_nop 0
	v_addc_co_u32_e32 v3, vcc, 0, v3, vcc
	global_load_dword v19, v[20:21], off nt
	s_nop 0
	global_load_dword v20, v[22:23], off nt
	global_load_dword v21, v[24:25], off nt
	s_nop 0
	global_load_dword v22, v[26:27], off nt
	global_load_dword v23, v[28:29], off nt
	global_load_dword v24, v[30:31], off nt
	global_load_dword v25, v[32:33], off nt
	s_nop 0
	global_load_dword v26, v[2:3], off nt
	v_and_b32_e32 v13, 56, v4
	v_mul_u32_u24_e32 v15, 0x41, v13
	v_lshlrev_b32_e32 v15, 2, v15
	v_lshlrev_b32_e32 v27, 2, v8
	v_lshlrev_b32_e32 v4, 1, v13
	v_add3_u32 v15, s33, v15, v27
	v_mul_u32_u24_e32 v27, 0x104, v6
	v_lshl_add_u64 v[2:3], s[20:21], 0, v[0:1]
	v_lshl_add_u64 v[4:5], s[0:1], 0, v[4:5]
	v_or_b32_e32 v13, 32, v8
	v_add3_u32 v0, s33, v27, v0
	v_readlane_b32 s5, v254, 60
	v_readlane_b32 s6, v254, 61
	v_readlane_b32 s7, v254, 62
	v_readlane_b32 s10, v255, 1
	v_readlane_b32 s11, v255, 2
	v_readlane_b32 s12, v255, 3
	v_readlane_b32 s13, v255, 4
	v_readlane_b32 s14, v255, 5
	v_readlane_b32 s15, v255, 6
	v_readlane_b32 s16, v255, 7
	v_readlane_b32 s17, v255, 8
	v_readlane_b32 s18, v255, 9
	v_readlane_b32 s19, v255, 10
	s_waitcnt vmcnt(0)
	s_branch .LBB0_1029

.LBB0_1031:
	v_mov_b32_e32 v4, v196
	v_readlane_b32 vcc_hi, v255, 44
	s_sub_i32 s0, s2, vcc_hi
	s_cmp_lt_i32 s0, 0
	s_cselect_b32 vcc_lo, s34, 0
	s_add_i32 s0, s0, vcc_lo
	s_add_i32 vcc_hi, vcc_hi, 128
	s_cmp_ge_u32 vcc_hi, s34
	s_cselect_b32 vcc_lo, s34, 0
	s_sub_i32 vcc_hi, vcc_hi, vcc_lo
	s_nop 0
	v_writelane_b32 v255, vcc_hi, 44
	v_mov_b32_e32 v0, v196
	s_lshl_b32 s0, s0, 1
	v_readfirstlane_b32 s1, v0
	s_ashr_i32 s1, s1, 8
	v_mov_b32_e32 v0, v196
	s_add_i32 s1, s1, s0
	s_lshl_b64 s[42:43], s[40:41], 20
	v_readfirstlane_b32 s0, v0
	s_ashr_i32 s0, s0, 8
	s_sub_i32 s22, s1, s0
	s_cmpk_gt_i32 s22, 0xff
	s_cbranch_scc1 .LBB0_1036
	v_readlane_b32 s4, v253, 14
	s_lshl_b64 s[0:1], s[42:43], 1
	v_readlane_b32 s8, v253, 18
	v_readlane_b32 s5, v253, 15
	v_readlane_b32 s6, v253, 16
	v_readlane_b32 s7, v253, 17
	v_readlane_b32 s9, v253, 19
	v_readlane_b32 s10, v253, 20
	v_readlane_b32 s11, v253, 21
	v_readlane_b32 s12, v253, 22
	v_readlane_b32 s13, v253, 23
	v_readlane_b32 s14, v253, 24
	v_readlane_b32 s15, v253, 25
	v_readlane_b32 s16, v253, 26
	v_readlane_b32 s17, v253, 27
	v_readlane_b32 s18, v253, 28
	v_readlane_b32 s19, v253, 29
	s_add_u32 s0, s8, s0
	s_addc_u32 s1, s9, s1
	v_readlane_b32 s4, v254, 59
	s_lshl_b64 s[20:21], s[42:43], 2
	v_readlane_b32 s10, v255, 1
	v_mov_b32_e32 v0, v196
	v_readlane_b32 s11, v255, 2
	s_add_u32 s20, s10, s20
	s_addc_u32 s21, s11, s21
	v_readfirstlane_b32 s23, v0
	s_ashr_i32 s23, s23, 8
	s_add_i32 s23, s23, s22
	s_min_i32 s23, s23, 0xff
	s_ashr_i32 s26, s23, 31
	s_lshr_b32 s26, s26, 28
	s_add_i32 s26, s23, s26
	s_and_b32 s27, s26, 0x3fffff0
	v_bfe_u32 v6, v4, 6, 2
	s_sub_i32 s23, s23, s27
	v_lshl_or_b32 v2, s23, 6, v6
	s_lshl_b32 s23, s26, 2
	s_and_b32 s26, s23, 0xffffffc0
	s_ashr_i32 s27, s26, 31
	s_lshl_b64 s[26:27], s[26:27], 2
	s_add_u32 s26, s20, s26
	v_lshlrev_b32_e32 v0, 2, v4
	s_waitcnt vmcnt(15)
	v_or_b32_e32 v10, 4, v2
	s_waitcnt vmcnt(13)
	v_or_b32_e32 v12, 8, v2
	s_waitcnt vmcnt(12)
	v_or_b32_e32 v14, 12, v2
	s_waitcnt vmcnt(0)
	v_or_b32_e32 v16, 16, v2
	v_or_b32_e32 v22, 20, v2
	v_or_b32_e32 v24, 24, v2
	v_or_b32_e32 v26, 28, v2
	s_addc_u32 s27, s21, s27
	v_and_b32_e32 v0, 0xfc, v0
	v_ashrrev_i32_e32 v3, 31, v2
	v_ashrrev_i32_e32 v11, 31, v10
	v_ashrrev_i32_e32 v13, 31, v12
	v_ashrrev_i32_e32 v15, 31, v14
	v_ashrrev_i32_e32 v17, 31, v16
	s_waitcnt lgkmcnt(4)
	v_ashrrev_i32_e32 v23, 31, v22
	v_ashrrev_i32_e32 v25, 31, v24
	v_ashrrev_i32_e32 v27, 31, v26
	v_lshl_add_u64 v[20:21], s[26:27], 0, v[0:1]
	v_lshlrev_b64 v[8:9], 12, v[2:3]
	v_lshlrev_b64 v[10:11], 12, v[10:11]
	v_lshlrev_b64 v[12:13], 12, v[12:13]
	v_lshlrev_b64 v[14:15], 12, v[14:15]
	v_lshlrev_b64 v[16:17], 12, v[16:17]
	v_lshlrev_b64 v[22:23], 12, v[22:23]
	v_lshlrev_b64 v[24:25], 12, v[24:25]
	v_lshlrev_b64 v[26:27], 12, v[26:27]
	v_lshl_add_u64 v[8:9], v[20:21], 0, v[8:9]
	v_lshl_add_u64 v[10:11], v[20:21], 0, v[10:11]
	v_lshl_add_u64 v[12:13], v[20:21], 0, v[12:13]
	v_lshl_add_u64 v[14:15], v[20:21], 0, v[14:15]
	v_lshl_add_u64 v[16:17], v[20:21], 0, v[16:17]
	v_lshl_add_u64 v[22:23], v[20:21], 0, v[22:23]
	v_lshl_add_u64 v[24:25], v[20:21], 0, v[24:25]
	v_lshl_add_u64 v[26:27], v[20:21], 0, v[26:27]
	global_load_dword v8, v[8:9], off nt
	s_nop 0
	global_load_dword v9, v[10:11], off nt
	s_nop 0
	global_load_dword v11, v[12:13], off nt
	s_nop 0
	global_load_dword v13, v[14:15], off nt
	s_nop 0
	global_load_dword v14, v[16:17], off nt
	global_load_dword v15, v[22:23], off nt
	s_nop 0
	global_load_dword v16, v[24:25], off nt
	global_load_dword v17, v[26:27], off nt
	v_or_b32_e32 v22, 32, v2
	v_or_b32_e32 v24, 36, v2
	v_or_b32_e32 v26, 40, v2
	v_ashrrev_i32_e32 v23, 31, v22
	v_ashrrev_i32_e32 v25, 31, v24
	v_ashrrev_i32_e32 v27, 31, v26
	v_or_b32_e32 v28, 44, v2
	v_or_b32_e32 v30, 48, v2
	s_waitcnt lgkmcnt(0)
	v_or_b32_e32 v32, 52, v2
	v_or_b32_e32 v34, 56, v2
	v_or_b32_e32 v2, 60, v2
	v_lshlrev_b64 v[22:23], 12, v[22:23]
	v_lshlrev_b64 v[24:25], 12, v[24:25]
	v_lshlrev_b64 v[26:27], 12, v[26:27]
	v_ashrrev_i32_e32 v29, 31, v28
	v_ashrrev_i32_e32 v31, 31, v30
	v_ashrrev_i32_e32 v33, 31, v32
	v_ashrrev_i32_e32 v35, 31, v34
	v_ashrrev_i32_e32 v3, 31, v2
	v_lshl_add_u64 v[22:23], v[20:21], 0, v[22:23]
	v_lshl_add_u64 v[24:25], v[20:21], 0, v[24:25]
	v_lshl_add_u64 v[26:27], v[20:21], 0, v[26:27]
	v_lshlrev_b64 v[28:29], 12, v[28:29]
	v_lshlrev_b64 v[30:31], 12, v[30:31]
	v_lshlrev_b64 v[32:33], 12, v[32:33]
	v_lshlrev_b64 v[34:35], 12, v[34:35]
	v_lshlrev_b64 v[2:3], 12, v[2:3]
	v_lshl_add_u64 v[28:29], v[20:21], 0, v[28:29]
	v_lshl_add_u64 v[30:31], v[20:21], 0, v[30:31]
	v_lshl_add_u64 v[32:33], v[20:21], 0, v[32:33]
	v_lshl_add_u64 v[34:35], v[20:21], 0, v[34:35]
	v_lshl_add_u64 v[2:3], v[20:21], 0, v[2:3]
	global_load_dword v19, v[22:23], off nt
	global_load_dword v20, v[24:25], off nt
	global_load_dword v21, v[26:27], off nt
	s_nop 0
	global_load_dword v22, v[28:29], off nt
	global_load_dword v23, v[30:31], off nt
	global_load_dword v24, v[32:33], off nt
	global_load_dword v25, v[34:35], off nt
	global_load_dword v26, v[2:3], off nt
	v_bfe_u32 v7, v4, 3, 5
	v_lshlrev_b32_e32 v4, 3, v4
	v_and_b32_e32 v10, 56, v4
	v_mul_u32_u24_e32 v12, 0x41, v10
	v_lshlrev_b32_e32 v12, 2, v12
	v_lshlrev_b32_e32 v27, 2, v7
	v_lshlrev_b32_e32 v4, 1, v10
	v_mov_b32_e32 v5, v1
	v_add3_u32 v12, s33, v12, v27
	v_mul_u32_u24_e32 v27, 0x104, v6
	v_lshl_add_u64 v[2:3], s[20:21], 0, v[0:1]
	v_lshl_add_u64 v[4:5], s[0:1], 0, v[4:5]
	v_or_b32_e32 v10, 32, v7
	v_add3_u32 v0, s33, v27, v0
	v_readlane_b32 s5, v254, 60
	v_readlane_b32 s6, v254, 61
	v_readlane_b32 s7, v254, 62
	v_readlane_b32 s8, v254, 63
	v_readlane_b32 s9, v255, 0
	v_readlane_b32 s12, v255, 3
	v_readlane_b32 s13, v255, 4
	v_readlane_b32 s14, v255, 5
	v_readlane_b32 s15, v255, 6
	v_readlane_b32 s16, v255, 7
	v_readlane_b32 s17, v255, 8
	v_readlane_b32 s18, v255, 9
	v_readlane_b32 s19, v255, 10
	s_waitcnt vmcnt(0)
	s_branch .LBB0_1034

.LBB0_1036:
	v_mov_b32_e32 v4, v196
	v_readlane_b32 vcc_hi, v255, 44
	s_sub_i32 s0, s2, vcc_hi
	s_cmp_lt_i32 s0, 0
	s_cselect_b32 vcc_lo, s34, 0
	s_add_i32 s0, s0, vcc_lo
	s_add_i32 vcc_hi, vcc_hi, 128
	s_cmp_ge_u32 vcc_hi, s34
	s_cselect_b32 vcc_lo, s34, 0
	s_sub_i32 vcc_hi, vcc_hi, vcc_lo
	s_nop 0
	v_writelane_b32 v255, vcc_hi, 44
	v_mov_b32_e32 v0, v196
	s_lshl_b32 s0, s0, 1
	v_readfirstlane_b32 s1, v0
	s_ashr_i32 s1, s1, 8
	v_mov_b32_e32 v0, v196
	s_add_i32 s1, s1, s0
	s_nop 0
	v_readfirstlane_b32 s0, v0
	s_ashr_i32 s0, s0, 8
	s_sub_i32 s22, s1, s0
	s_cmpk_gt_i32 s22, 0x2ff
	s_cbranch_scc1 .LBB0_1041
	v_readlane_b32 s4, v253, 14
	s_mul_i32 s0, s40, 0x600000
	v_readlane_b32 s12, v253, 22
	v_readlane_b32 s13, v253, 23
	s_add_u32 s0, s12, s0
	s_addc_u32 s1, s13, 0
	s_mul_i32 s20, s40, 0xc00000
	v_mov_b32_e32 v0, v196
	s_add_u32 s20, s74, s20
	s_addc_u32 s21, s75, 0
	v_readfirstlane_b32 s23, v0
	s_ashr_i32 s23, s23, 8
	s_add_i32 s23, s23, s22
	s_min_i32 s23, s23, 0x2ff
	s_ashr_i32 s26, s23, 31
	s_lshr_b32 s26, s26, 28
	s_add_i32 s26, s23, s26
	s_and_b32 s27, s26, 0xfff0
	v_bfe_u32 v6, v4, 6, 2
	s_sub_i32 s23, s23, s27
	v_lshl_or_b32 v5, s23, 6, v6
	s_lshl_b32 s23, s26, 2
	s_and_b32 s26, s23, 0xffffffc0
	s_ashr_i32 s27, s26, 31
	s_lshl_b64 s[26:27], s[26:27], 2
	s_add_u32 s26, s20, s26
	v_lshlrev_b32_e32 v0, 2, v4
	s_addc_u32 s27, s21, s27
	v_and_b32_e32 v0, 0xfc, v0
	s_waitcnt vmcnt(1)
	v_mul_lo_u32 v8, v5, s47
	v_lshl_add_u64 v[2:3], s[26:27], 0, v[0:1]
	v_ashrrev_i32_e32 v9, 31, v8
	v_lshl_add_u64 v[2:3], v[8:9], 2, v[2:3]
	v_add_co_u32_e32 v10, vcc, s36, v2
	s_mov_b32 s4, 0x60000
	s_nop 0
	v_addc_co_u32_e32 v11, vcc, 0, v3, vcc
	v_add_co_u32_e32 v12, vcc, s35, v2
	s_mov_b32 s23, 0x6c000
	s_nop 0
	v_addc_co_u32_e32 v13, vcc, 0, v3, vcc
	v_add_co_u32_e32 v14, vcc, s51, v2
	v_bfe_u32 v7, v4, 3, 5
	s_nop 0
	v_addc_co_u32_e32 v15, vcc, 0, v3, vcc
	s_waitcnt vmcnt(0)
	v_add_co_u32_e32 v16, vcc, s52, v2
	v_lshlrev_b32_e32 v4, 3, v4
	s_nop 0
	v_addc_co_u32_e32 v17, vcc, 0, v3, vcc
	v_add_co_u32_e32 v20, vcc, s96, v2
	v_and_b32_e32 v9, 56, v4
	s_nop 0
	v_addc_co_u32_e32 v21, vcc, 0, v3, vcc
	v_add_co_u32_e32 v22, vcc, s46, v2
	v_lshlrev_b32_e32 v4, 1, v9
	s_waitcnt lgkmcnt(4)
	v_addc_co_u32_e32 v23, vcc, 0, v3, vcc
	v_add_co_u32_e32 v24, vcc, s97, v2
	v_mov_b32_e32 v5, v1
	s_nop 0
	v_addc_co_u32_e32 v25, vcc, 0, v3, vcc
	global_load_dword v8, v[2:3], off nt
	s_nop 0
	global_load_dword v10, v[10:11], off nt
	s_nop 0
	global_load_dword v12, v[12:13], off nt
	s_nop 0
	global_load_dword v13, v[14:15], off nt
	s_nop 0
	global_load_dword v14, v[16:17], off nt
	global_load_dword v15, v[20:21], off nt
	s_nop 0
	global_load_dword v16, v[22:23], off nt
	global_load_dword v17, v[24:25], off nt
	v_add_co_u32_e32 v20, vcc, s4, v2
	s_mov_b32 s4, 0x84000
	s_nop 0
	v_addc_co_u32_e32 v21, vcc, 0, v3, vcc
	v_add_co_u32_e32 v22, vcc, s23, v2
	s_mov_b32 s23, 0x78000
	s_nop 0
	v_addc_co_u32_e32 v23, vcc, 0, v3, vcc
	v_add_co_u32_e32 v24, vcc, s23, v2
	s_mov_b32 s23, 0x90000
	s_nop 0
	v_addc_co_u32_e32 v25, vcc, 0, v3, vcc
	v_add_co_u32_e32 v26, vcc, s4, v2
	s_mov_b32 s4, 0x9c000
	s_nop 0
	v_addc_co_u32_e32 v27, vcc, 0, v3, vcc
	v_add_co_u32_e32 v28, vcc, s23, v2
	s_mov_b32 s23, 0xa8000
	s_nop 0
	v_addc_co_u32_e32 v29, vcc, 0, v3, vcc
	v_add_co_u32_e32 v30, vcc, s4, v2
	v_mul_u32_u24_e32 v11, 0x41, v9
	s_nop 0
	v_addc_co_u32_e32 v31, vcc, 0, v3, vcc
	s_waitcnt lgkmcnt(0)
	v_add_co_u32_e32 v32, vcc, s23, v2
	s_mov_b32 s23, 0xb4000
	s_nop 0
	v_addc_co_u32_e32 v33, vcc, 0, v3, vcc
	v_add_co_u32_e32 v2, vcc, s23, v2
	v_lshlrev_b32_e32 v11, 2, v11
	s_nop 0
	v_addc_co_u32_e32 v3, vcc, 0, v3, vcc
	global_load_dword v19, v[20:21], off nt
	s_nop 0
	global_load_dword v20, v[22:23], off nt
	global_load_dword v21, v[24:25], off nt
	s_nop 0
	global_load_dword v22, v[26:27], off nt
	global_load_dword v23, v[28:29], off nt
	global_load_dword v24, v[30:31], off nt
	global_load_dword v25, v[32:33], off nt
	s_nop 0
	global_load_dword v26, v[2:3], off nt
	v_lshlrev_b32_e32 v27, 2, v7
	v_add3_u32 v11, s33, v11, v27
	v_mul_u32_u24_e32 v27, 0x104, v6
	v_lshl_add_u64 v[2:3], s[20:21], 0, v[0:1]
	v_lshl_add_u64 v[4:5], s[0:1], 0, v[4:5]
	v_or_b32_e32 v9, 32, v7
	v_add3_u32 v0, s33, v27, v0
	v_readlane_b32 s5, v253, 15
	v_readlane_b32 s6, v253, 16
	v_readlane_b32 s7, v253, 17
	v_readlane_b32 s8, v253, 18
	v_readlane_b32 s9, v253, 19
	v_readlane_b32 s10, v253, 20
	v_readlane_b32 s11, v253, 21
	v_readlane_b32 s14, v253, 24
	v_readlane_b32 s15, v253, 25
	v_readlane_b32 s16, v253, 26
	v_readlane_b32 s17, v253, 27
	v_readlane_b32 s18, v253, 28
	v_readlane_b32 s19, v253, 29
	s_waitcnt vmcnt(0)
	s_branch .LBB0_1039

.LBB0_1041:
	v_mov_b32_e32 v4, v196
	v_readlane_b32 vcc_hi, v255, 44
	s_sub_i32 s0, s2, vcc_hi
	s_cmp_lt_i32 s0, 0
	s_cselect_b32 vcc_lo, s34, 0
	s_add_i32 s0, s0, vcc_lo
	s_add_i32 vcc_hi, vcc_hi, 128
	s_cmp_ge_u32 vcc_hi, s34
	s_cselect_b32 vcc_lo, s34, 0
	s_sub_i32 vcc_hi, vcc_hi, vcc_lo
	s_nop 0
	v_writelane_b32 v255, vcc_hi, 44
	v_mov_b32_e32 v0, v196
	s_lshl_b32 s0, s0, 1
	v_readfirstlane_b32 s1, v0
	s_ashr_i32 s1, s1, 8
	v_mov_b32_e32 v0, v196
	s_add_i32 s1, s1, s0
	s_nop 0
	v_readfirstlane_b32 s0, v0
	s_ashr_i32 s0, s0, 8
	s_sub_i32 s22, s1, s0
	s_cmpk_gt_i32 s22, 0xff
	s_cbranch_scc1 .LBB0_1025
	v_readlane_b32 s4, v253, 14
	s_lshl_b64 s[0:1], s[42:43], 1
	v_readlane_b32 s14, v253, 24
	v_readlane_b32 s15, v253, 25
	s_add_u32 s0, s14, s0
	s_addc_u32 s1, s15, s1
	s_lshl_b64 s[20:21], s[42:43], 2
	v_mov_b32_e32 v0, v196
	s_add_u32 s20, s68, s20
	s_addc_u32 s21, s69, s21
	v_readfirstlane_b32 s23, v0
	s_ashr_i32 s23, s23, 8
	s_add_i32 s23, s23, s22
	s_min_i32 s23, s23, 0xff
	s_ashr_i32 s26, s23, 31
	s_lshr_b32 s26, s26, 28
	s_add_i32 s26, s23, s26
	s_and_b32 s27, s26, 0x3fffff0
	v_bfe_u32 v6, v4, 6, 2
	s_sub_i32 s23, s23, s27
	v_lshl_or_b32 v2, s23, 6, v6
	s_lshl_b32 s23, s26, 2
	s_and_b32 s26, s23, 0xffffffc0
	s_ashr_i32 s27, s26, 31
	s_lshl_b64 s[26:27], s[26:27], 2
	s_add_u32 s26, s20, s26
	v_lshlrev_b32_e32 v0, 2, v4
	s_waitcnt vmcnt(15)
	v_or_b32_e32 v10, 4, v2
	s_waitcnt vmcnt(13)
	v_or_b32_e32 v12, 8, v2
	s_waitcnt vmcnt(12)
	v_or_b32_e32 v14, 12, v2
	s_waitcnt vmcnt(0)
	v_or_b32_e32 v16, 16, v2
	v_or_b32_e32 v22, 20, v2
	v_or_b32_e32 v24, 24, v2
	v_or_b32_e32 v26, 28, v2
	s_addc_u32 s27, s21, s27
	v_and_b32_e32 v0, 0xfc, v0
	v_ashrrev_i32_e32 v3, 31, v2
	v_ashrrev_i32_e32 v11, 31, v10
	v_ashrrev_i32_e32 v13, 31, v12
	v_ashrrev_i32_e32 v15, 31, v14
	v_ashrrev_i32_e32 v17, 31, v16
	s_waitcnt lgkmcnt(4)
	v_ashrrev_i32_e32 v23, 31, v22
	v_ashrrev_i32_e32 v25, 31, v24
	v_ashrrev_i32_e32 v27, 31, v26
	v_lshl_add_u64 v[20:21], s[26:27], 0, v[0:1]
	v_lshlrev_b64 v[8:9], 12, v[2:3]
	v_lshlrev_b64 v[10:11], 12, v[10:11]
	v_lshlrev_b64 v[12:13], 12, v[12:13]
	v_lshlrev_b64 v[14:15], 12, v[14:15]
	v_lshlrev_b64 v[16:17], 12, v[16:17]
	v_lshlrev_b64 v[22:23], 12, v[22:23]
	v_lshlrev_b64 v[24:25], 12, v[24:25]
	v_lshlrev_b64 v[26:27], 12, v[26:27]
	v_lshl_add_u64 v[8:9], v[20:21], 0, v[8:9]
	v_lshl_add_u64 v[10:11], v[20:21], 0, v[10:11]
	v_lshl_add_u64 v[12:13], v[20:21], 0, v[12:13]
	v_lshl_add_u64 v[14:15], v[20:21], 0, v[14:15]
	v_lshl_add_u64 v[16:17], v[20:21], 0, v[16:17]
	v_lshl_add_u64 v[22:23], v[20:21], 0, v[22:23]
	v_lshl_add_u64 v[24:25], v[20:21], 0, v[24:25]
	v_lshl_add_u64 v[26:27], v[20:21], 0, v[26:27]
	global_load_dword v8, v[8:9], off nt
	s_nop 0
	global_load_dword v9, v[10:11], off nt
	s_nop 0
	global_load_dword v11, v[12:13], off nt
	s_nop 0
	global_load_dword v13, v[14:15], off nt
	s_nop 0
	global_load_dword v14, v[16:17], off nt
	global_load_dword v15, v[22:23], off nt
	s_nop 0
	global_load_dword v16, v[24:25], off nt
	global_load_dword v17, v[26:27], off nt
	v_or_b32_e32 v22, 32, v2
	v_or_b32_e32 v24, 36, v2
	v_or_b32_e32 v26, 40, v2
	v_ashrrev_i32_e32 v23, 31, v22
	v_ashrrev_i32_e32 v25, 31, v24
	v_ashrrev_i32_e32 v27, 31, v26
	v_or_b32_e32 v28, 44, v2
	v_or_b32_e32 v30, 48, v2
	s_waitcnt lgkmcnt(0)
	v_or_b32_e32 v32, 52, v2
	v_or_b32_e32 v34, 56, v2
	v_or_b32_e32 v2, 60, v2
	v_lshlrev_b64 v[22:23], 12, v[22:23]
	v_lshlrev_b64 v[24:25], 12, v[24:25]
	v_lshlrev_b64 v[26:27], 12, v[26:27]
	v_ashrrev_i32_e32 v29, 31, v28
	v_ashrrev_i32_e32 v31, 31, v30
	v_ashrrev_i32_e32 v33, 31, v32
	v_ashrrev_i32_e32 v35, 31, v34
	v_ashrrev_i32_e32 v3, 31, v2
	v_lshl_add_u64 v[22:23], v[20:21], 0, v[22:23]
	v_lshl_add_u64 v[24:25], v[20:21], 0, v[24:25]
	v_lshl_add_u64 v[26:27], v[20:21], 0, v[26:27]
	v_lshlrev_b64 v[28:29], 12, v[28:29]
	v_lshlrev_b64 v[30:31], 12, v[30:31]
	v_lshlrev_b64 v[32:33], 12, v[32:33]
	v_lshlrev_b64 v[34:35], 12, v[34:35]
	v_lshlrev_b64 v[2:3], 12, v[2:3]
	v_lshl_add_u64 v[28:29], v[20:21], 0, v[28:29]
	v_lshl_add_u64 v[30:31], v[20:21], 0, v[30:31]
	v_lshl_add_u64 v[32:33], v[20:21], 0, v[32:33]
	v_lshl_add_u64 v[34:35], v[20:21], 0, v[34:35]
	v_lshl_add_u64 v[2:3], v[20:21], 0, v[2:3]
	global_load_dword v19, v[22:23], off nt
	global_load_dword v20, v[24:25], off nt
	global_load_dword v21, v[26:27], off nt
	s_nop 0
	global_load_dword v22, v[28:29], off nt
	global_load_dword v23, v[30:31], off nt
	global_load_dword v24, v[32:33], off nt
	global_load_dword v25, v[34:35], off nt
	global_load_dword v26, v[2:3], off nt
	v_bfe_u32 v7, v4, 3, 5
	v_lshlrev_b32_e32 v4, 3, v4
	v_and_b32_e32 v10, 56, v4
	v_mul_u32_u24_e32 v12, 0x41, v10
	v_lshlrev_b32_e32 v12, 2, v12
	v_lshlrev_b32_e32 v27, 2, v7
	v_lshlrev_b32_e32 v4, 1, v10
	v_mov_b32_e32 v5, v1
	v_add3_u32 v12, s33, v12, v27
	v_mul_u32_u24_e32 v27, 0x104, v6
	v_lshl_add_u64 v[2:3], s[20:21], 0, v[0:1]
	v_lshl_add_u64 v[4:5], s[0:1], 0, v[4:5]
	v_or_b32_e32 v10, 32, v7
	v_add3_u32 v0, s33, v27, v0
	v_readlane_b32 s5, v253, 15
	v_readlane_b32 s6, v253, 16
	v_readlane_b32 s7, v253, 17
	v_readlane_b32 s8, v253, 18
	v_readlane_b32 s9, v253, 19
	v_readlane_b32 s10, v253, 20
	v_readlane_b32 s11, v253, 21
	v_readlane_b32 s12, v253, 22
	v_readlane_b32 s13, v253, 23
	v_readlane_b32 s16, v253, 26
	v_readlane_b32 s17, v253, 27
	v_readlane_b32 s18, v253, 28
	v_readlane_b32 s19, v253, 29
	s_waitcnt vmcnt(0)
	s_branch .LBB0_1044

.LBB0_1058:
	v_mov_b32_e32 v4, v196
	v_readlane_b32 vcc_hi, v255, 44
	s_sub_i32 s0, s2, vcc_hi
	s_cmp_lt_i32 s0, 0
	s_cselect_b32 vcc_lo, s34, 0
	s_add_i32 s0, s0, vcc_lo
	s_add_i32 vcc_hi, vcc_hi, 96
	s_cmp_ge_u32 vcc_hi, s34
	s_cselect_b32 vcc_lo, s34, 0
	s_sub_i32 vcc_hi, vcc_hi, vcc_lo
	s_nop 0
	v_writelane_b32 v255, vcc_hi, 44
	v_mov_b32_e32 v0, v196
	s_lshl_b32 s0, s0, 1
	v_readfirstlane_b32 s20, v0
	s_ashr_i32 s20, s20, 8
	v_mov_b32_e32 v0, v196
	s_add_i32 s20, s20, s0
	s_mul_hi_u32 s29, s26, 0x2c0000
	v_readfirstlane_b32 s0, v0
	s_ashr_i32 s0, s0, 8
	s_sub_i32 s27, s20, s0
	s_mul_i32 s28, s26, 0x2c0000
	s_mul_hi_u32 s1, s26, 0x580000
	s_cmpk_gt_i32 s27, 0x2bf
	s_mul_i32 s0, s26, 0x580000
	s_cbranch_scc1 .LBB0_1063
	v_readlane_b32 s4, v253, 14
	s_lshl_b64 s[20:21], s[0:1], 1
	v_readlane_b32 s16, v253, 26
	v_readlane_b32 s5, v253, 15
	v_readlane_b32 s6, v253, 16
	v_readlane_b32 s7, v253, 17
	v_readlane_b32 s8, v253, 18
	v_readlane_b32 s9, v253, 19
	v_readlane_b32 s10, v253, 20
	v_readlane_b32 s11, v253, 21
	v_readlane_b32 s12, v253, 22
	v_readlane_b32 s13, v253, 23
	v_readlane_b32 s14, v253, 24
	v_readlane_b32 s15, v253, 25
	v_readlane_b32 s17, v253, 27
	v_readlane_b32 s18, v253, 28
	v_readlane_b32 s19, v253, 29
	s_add_u32 s20, s16, s20
	s_addc_u32 s21, s17, s21
	v_readlane_b32 s4, v254, 27
	s_lshl_b64 s[22:23], s[28:29], 2
	v_readlane_b32 s16, v254, 39
	v_mov_b32_e32 v0, v196
	v_readlane_b32 s17, v254, 40
	s_add_u32 s22, s16, s22
	s_addc_u32 s23, s17, s23
	v_readfirstlane_b32 s40, v0
	s_ashr_i32 s40, s40, 8
	s_add_i32 s40, s40, s27
	s_min_i32 s40, s40, 0x2bf
	s_ashr_i32 s41, s40, 31
	s_lshr_b32 s41, s41, 28
	s_add_i32 s41, s40, s41
	s_and_b32 s42, s41, 0x3fff0
	v_bfe_u32 v6, v4, 6, 2
	s_sub_i32 s40, s40, s42
	v_lshl_or_b32 v5, s40, 6, v6
	s_lshl_b32 s40, s41, 2
	s_andn2_b32 s40, s40, 63
	s_ashr_i32 s41, s40, 31
	s_lshl_b64 s[40:41], s[40:41], 2
	s_add_u32 s40, s22, s40
	v_lshlrev_b32_e32 v0, 2, v4
	s_addc_u32 s41, s23, s41
	v_and_b32_e32 v0, 0xfc, v0
	s_waitcnt vmcnt(1)
	v_mul_lo_u32 v8, v5, s49
	v_lshl_add_u64 v[2:3], s[40:41], 0, v[0:1]
	v_ashrrev_i32_e32 v9, 31, v8
	v_lshl_add_u64 v[2:3], v[8:9], 2, v[2:3]
	v_add_co_u32_e32 v10, vcc, s43, v2
	s_mov_b32 s4, 0x63000
	s_nop 0
	v_addc_co_u32_e32 v11, vcc, 0, v3, vcc
	v_add_co_u32_e32 v12, vcc, s44, v2
	v_bfe_u32 v7, v4, 3, 5
	s_nop 0
	v_addc_co_u32_e32 v13, vcc, 0, v3, vcc
	v_add_co_u32_e32 v14, vcc, s45, v2
	v_lshlrev_b32_e32 v4, 3, v4
	s_nop 0
	v_addc_co_u32_e32 v15, vcc, 0, v3, vcc
	s_waitcnt vmcnt(0)
	v_add_co_u32_e32 v16, vcc, s47, v2
	v_mov_b32_e32 v5, v1
	s_nop 0
	v_addc_co_u32_e32 v17, vcc, 0, v3, vcc
	v_add_co_u32_e32 v20, vcc, s48, v2
	v_readlane_b32 s5, v254, 28
	s_nop 0
	v_addc_co_u32_e32 v21, vcc, 0, v3, vcc
	v_add_co_u32_e32 v22, vcc, s38, v2
	v_readlane_b32 s6, v254, 29
	s_waitcnt lgkmcnt(4)
	v_addc_co_u32_e32 v23, vcc, 0, v3, vcc
	v_add_co_u32_e32 v24, vcc, s50, v2
	v_readlane_b32 s7, v254, 30
	s_nop 0
	v_addc_co_u32_e32 v25, vcc, 0, v3, vcc
	global_load_dword v8, v[2:3], off nt
	global_load_dword v9, v[10:11], off nt
	s_nop 0
	global_load_dword v11, v[12:13], off nt
	s_nop 0
	global_load_dword v13, v[14:15], off nt
	s_nop 0
	global_load_dword v14, v[16:17], off nt
	global_load_dword v15, v[20:21], off nt
	s_nop 0
	global_load_dword v16, v[22:23], off nt
	global_load_dword v17, v[24:25], off nt
	v_add_co_u32_e32 v20, vcc, s51, v2
	v_and_b32_e32 v10, 56, v4
	s_nop 0
	v_addc_co_u32_e32 v21, vcc, 0, v3, vcc
	v_add_co_u32_e32 v22, vcc, s4, v2
	s_mov_b32 s4, 0x6e000
	s_nop 0
	v_addc_co_u32_e32 v23, vcc, 0, v3, vcc
	v_add_co_u32_e32 v24, vcc, s4, v2
	s_mov_b32 s4, 0x79000
	s_nop 0
	v_addc_co_u32_e32 v25, vcc, 0, v3, vcc
	v_add_co_u32_e32 v26, vcc, s4, v2
	s_mov_b32 s4, 0x8f000
	s_nop 0
	v_addc_co_u32_e32 v27, vcc, 0, v3, vcc
	v_add_co_u32_e32 v28, vcc, s46, v2
	v_mul_u32_u24_e32 v12, 0x41, v10
	s_nop 0
	v_addc_co_u32_e32 v29, vcc, 0, v3, vcc
	v_add_co_u32_e32 v30, vcc, s4, v2
	s_mov_b32 s4, 0x9a000
	s_nop 0
	v_addc_co_u32_e32 v31, vcc, 0, v3, vcc
	s_waitcnt lgkmcnt(0)
	v_add_co_u32_e32 v32, vcc, s4, v2
	s_mov_b32 s4, 0xa5000
	s_nop 0
	v_addc_co_u32_e32 v33, vcc, 0, v3, vcc
	v_add_co_u32_e32 v2, vcc, s4, v2
	v_lshlrev_b32_e32 v12, 2, v12
	s_nop 0
	v_addc_co_u32_e32 v3, vcc, 0, v3, vcc
	global_load_dword v19, v[20:21], off nt
	s_nop 0
	global_load_dword v20, v[22:23], off nt
	global_load_dword v21, v[24:25], off nt
	s_nop 0
	global_load_dword v22, v[26:27], off nt
	global_load_dword v23, v[28:29], off nt
	global_load_dword v24, v[30:31], off nt
	global_load_dword v25, v[32:33], off nt
	s_nop 0
	global_load_dword v26, v[2:3], off nt
	v_lshlrev_b32_e32 v27, 2, v7
	v_lshlrev_b32_e32 v4, 1, v10
	v_add3_u32 v12, s33, v12, v27
	v_mul_u32_u24_e32 v27, 0x104, v6
	v_lshl_add_u64 v[2:3], s[22:23], 0, v[0:1]
	v_lshl_add_u64 v[4:5], s[20:21], 0, v[4:5]
	v_or_b32_e32 v10, 32, v7
	v_add3_u32 v0, s33, v27, v0
	v_readlane_b32 s8, v254, 31
	v_readlane_b32 s9, v254, 32
	v_readlane_b32 s10, v254, 33
	v_readlane_b32 s11, v254, 34
	v_readlane_b32 s12, v254, 35
	v_readlane_b32 s13, v254, 36
	v_readlane_b32 s14, v254, 37
	v_readlane_b32 s15, v254, 38
	v_readlane_b32 s18, v254, 41
	v_readlane_b32 s19, v254, 42
	s_waitcnt vmcnt(0)
	s_branch .LBB0_1061

.LBB0_1063:
	v_mov_b32_e32 v4, v196
	v_readlane_b32 vcc_hi, v255, 44
	s_sub_i32 s20, s2, vcc_hi
	s_cmp_lt_i32 s20, 0
	s_cselect_b32 vcc_lo, s34, 0
	s_add_i32 s20, s20, vcc_lo
	s_add_i32 vcc_hi, vcc_hi, 96
	s_cmp_ge_u32 vcc_hi, s34
	s_cselect_b32 vcc_lo, s34, 0
	s_sub_i32 vcc_hi, vcc_hi, vcc_lo
	s_nop 0
	v_writelane_b32 v255, vcc_hi, 44
	v_mov_b32_e32 v0, v196
	s_lshl_b32 s20, s20, 1
	v_readfirstlane_b32 s21, v0
	s_ashr_i32 s21, s21, 8
	v_mov_b32_e32 v0, v196
	s_add_i32 s21, s21, s20
	s_nop 0
	v_readfirstlane_b32 s20, v0
	s_ashr_i32 s20, s20, 8
	s_sub_i32 s22, s21, s20
	s_cmpk_gt_i32 s22, 0x2bf
	s_cbranch_scc1 .LBB0_1068
	v_readlane_b32 s4, v253, 14
	s_lshl_b64 s[0:1], s[0:1], 1
	v_readlane_b32 s16, v253, 26
	v_readlane_b32 s5, v253, 15
	v_readlane_b32 s6, v253, 16
	v_readlane_b32 s7, v253, 17
	v_readlane_b32 s8, v253, 18
	v_readlane_b32 s9, v253, 19
	v_readlane_b32 s10, v253, 20
	v_readlane_b32 s11, v253, 21
	v_readlane_b32 s12, v253, 22
	v_readlane_b32 s13, v253, 23
	v_readlane_b32 s14, v253, 24
	v_readlane_b32 s15, v253, 25
	v_readlane_b32 s17, v253, 27
	v_readlane_b32 s18, v253, 28
	v_readlane_b32 s19, v253, 29
	s_add_u32 s0, s16, s0
	s_addc_u32 s1, s17, s1
	v_readlane_b32 s4, v254, 27
	s_lshl_b64 s[20:21], s[28:29], 2
	v_readlane_b32 s18, v254, 41
	v_mov_b32_e32 v0, v196
	v_readlane_b32 s19, v254, 42
	s_add_u32 s20, s18, s20
	s_addc_u32 s21, s19, s21
	v_readfirstlane_b32 s23, v0
	s_ashr_i32 s23, s23, 8
	s_add_i32 s23, s23, s22
	s_min_i32 s23, s23, 0x2bf
	s_ashr_i32 s27, s23, 31
	s_lshr_b32 s27, s27, 28
	s_add_i32 s27, s23, s27
	s_and_b32 s40, s27, 0x3fff0
	v_bfe_u32 v6, v4, 6, 2
	s_sub_i32 s23, s23, s40
	v_lshl_or_b32 v5, s23, 6, v6
	s_lshl_b32 s23, s27, 2
	s_and_b32 s40, s23, 0xffffffc0
	s_ashr_i32 s41, s40, 31
	s_lshl_b64 s[40:41], s[40:41], 2
	s_add_u32 s40, s20, s40
	v_lshlrev_b32_e32 v0, 2, v4
	s_addc_u32 s41, s21, s41
	v_and_b32_e32 v0, 0xfc, v0
	s_waitcnt vmcnt(1)
	v_mul_lo_u32 v8, v5, s49
	v_lshl_add_u64 v[2:3], s[40:41], 0, v[0:1]
	v_ashrrev_i32_e32 v9, 31, v8
	v_lshl_add_u64 v[2:3], v[8:9], 2, v[2:3]
	v_add_co_u32_e32 v10, vcc, s43, v2
	s_mov_b32 s4, 0x63000
	s_nop 0
	v_addc_co_u32_e32 v11, vcc, 0, v3, vcc
	v_add_co_u32_e32 v12, vcc, s44, v2
	v_bfe_u32 v7, v4, 3, 5
	s_nop 0
	v_addc_co_u32_e32 v13, vcc, 0, v3, vcc
	v_add_co_u32_e32 v14, vcc, s45, v2
	v_lshlrev_b32_e32 v4, 3, v4
	s_nop 0
	v_addc_co_u32_e32 v15, vcc, 0, v3, vcc
	s_waitcnt vmcnt(0)
	v_add_co_u32_e32 v16, vcc, s47, v2
	v_mov_b32_e32 v5, v1
	s_nop 0
	v_addc_co_u32_e32 v17, vcc, 0, v3, vcc
	v_add_co_u32_e32 v20, vcc, s48, v2
	v_readlane_b32 s5, v254, 28
	s_nop 0
	v_addc_co_u32_e32 v21, vcc, 0, v3, vcc
	v_add_co_u32_e32 v22, vcc, s38, v2
	v_readlane_b32 s6, v254, 29
	s_waitcnt lgkmcnt(4)
	v_addc_co_u32_e32 v23, vcc, 0, v3, vcc
	v_add_co_u32_e32 v24, vcc, s50, v2
	v_readlane_b32 s7, v254, 30
	s_nop 0
	v_addc_co_u32_e32 v25, vcc, 0, v3, vcc
	global_load_dword v8, v[2:3], off nt
	global_load_dword v9, v[10:11], off nt
	s_nop 0
	global_load_dword v11, v[12:13], off nt
	s_nop 0
	global_load_dword v13, v[14:15], off nt
	s_nop 0
	global_load_dword v14, v[16:17], off nt
	global_load_dword v15, v[20:21], off nt
	s_nop 0
	global_load_dword v16, v[22:23], off nt
	global_load_dword v17, v[24:25], off nt
	v_add_co_u32_e32 v20, vcc, s51, v2
	v_and_b32_e32 v10, 56, v4
	s_nop 0
	v_addc_co_u32_e32 v21, vcc, 0, v3, vcc
	v_add_co_u32_e32 v22, vcc, s4, v2
	s_mov_b32 s4, 0x6e000
	s_nop 0
	v_addc_co_u32_e32 v23, vcc, 0, v3, vcc
	v_add_co_u32_e32 v24, vcc, s4, v2
	s_mov_b32 s4, 0x79000
	s_nop 0
	v_addc_co_u32_e32 v25, vcc, 0, v3, vcc
	v_add_co_u32_e32 v26, vcc, s4, v2
	s_mov_b32 s4, 0x8f000
	s_nop 0
	v_addc_co_u32_e32 v27, vcc, 0, v3, vcc
	v_add_co_u32_e32 v28, vcc, s46, v2
	v_mul_u32_u24_e32 v12, 0x41, v10
	s_nop 0
	v_addc_co_u32_e32 v29, vcc, 0, v3, vcc
	v_add_co_u32_e32 v30, vcc, s4, v2
	s_mov_b32 s4, 0x9a000
	s_nop 0
	v_addc_co_u32_e32 v31, vcc, 0, v3, vcc
	s_waitcnt lgkmcnt(0)
	v_add_co_u32_e32 v32, vcc, s4, v2
	s_mov_b32 s4, 0xa5000
	s_nop 0
	v_addc_co_u32_e32 v33, vcc, 0, v3, vcc
	v_add_co_u32_e32 v2, vcc, s4, v2
	v_lshlrev_b32_e32 v12, 2, v12
	s_nop 0
	v_addc_co_u32_e32 v3, vcc, 0, v3, vcc
	global_load_dword v19, v[20:21], off nt
	s_nop 0
	global_load_dword v20, v[22:23], off nt
	global_load_dword v21, v[24:25], off nt
	s_nop 0
	global_load_dword v22, v[26:27], off nt
	global_load_dword v23, v[28:29], off nt
	global_load_dword v24, v[30:31], off nt
	global_load_dword v25, v[32:33], off nt
	s_nop 0
	global_load_dword v26, v[2:3], off nt
	v_lshlrev_b32_e32 v27, 2, v7
	v_lshlrev_b32_e32 v4, 1, v10
	v_add3_u32 v12, s33, v12, v27
	v_mul_u32_u24_e32 v27, 0x104, v6
	v_lshl_add_u64 v[2:3], s[20:21], 0, v[0:1]
	v_lshl_add_u64 v[4:5], s[0:1], 0, v[4:5]
	v_or_b32_e32 v10, 32, v7
	v_add3_u32 v0, s33, v27, v0
	v_readlane_b32 s8, v254, 31
	v_readlane_b32 s9, v254, 32
	v_readlane_b32 s10, v254, 33
	v_readlane_b32 s11, v254, 34
	v_readlane_b32 s12, v254, 35
	v_readlane_b32 s13, v254, 36
	v_readlane_b32 s14, v254, 37
	v_readlane_b32 s15, v254, 38
	v_readlane_b32 s16, v254, 39
	v_readlane_b32 s17, v254, 40
	s_waitcnt vmcnt(0)
	s_branch .LBB0_1066

.LBB0_1068:
	v_mov_b32_e32 v4, v196
	v_readlane_b32 vcc_hi, v255, 44
	s_sub_i32 s0, s2, vcc_hi
	s_cmp_lt_i32 s0, 0
	s_cselect_b32 vcc_lo, s34, 0
	s_add_i32 s0, s0, vcc_lo
	s_add_i32 vcc_hi, vcc_hi, 96
	s_cmp_ge_u32 vcc_hi, s34
	s_cselect_b32 vcc_lo, s34, 0
	s_sub_i32 vcc_hi, vcc_hi, vcc_lo
	s_nop 0
	v_writelane_b32 v255, vcc_hi, 44
	v_mov_b32_e32 v0, v196
	s_lshl_b32 s0, s0, 1
	v_readfirstlane_b32 s1, v0
	s_ashr_i32 s1, s1, 8
	v_mov_b32_e32 v0, v196
	s_add_i32 s1, s1, s0
	s_nop 0
	v_readfirstlane_b32 s0, v0
	s_ashr_i32 s0, s0, 8
	s_sub_i32 s22, s1, s0
	s_cmpk_gt_i32 s22, 0x2bf
	s_cbranch_scc1 .LBB0_1057
	v_readlane_b32 s4, v253, 14
	s_lshl_b64 s[0:1], s[28:29], 1
	v_readlane_b32 s18, v253, 28
	v_readlane_b32 s5, v253, 15
	v_readlane_b32 s6, v253, 16
	v_readlane_b32 s7, v253, 17
	v_readlane_b32 s8, v253, 18
	v_readlane_b32 s9, v253, 19
	v_readlane_b32 s10, v253, 20
	v_readlane_b32 s11, v253, 21
	v_readlane_b32 s12, v253, 22
	v_readlane_b32 s13, v253, 23
	v_readlane_b32 s14, v253, 24
	v_readlane_b32 s15, v253, 25
	v_readlane_b32 s16, v253, 26
	v_readlane_b32 s17, v253, 27
	v_readlane_b32 s19, v253, 29
	s_add_u32 s0, s18, s0
	s_addc_u32 s1, s19, s1
	s_mul_i32 s20, s26, 0xb00000
	v_readlane_b32 s4, v254, 59
	v_mov_b32_e32 v0, v196
	s_mul_hi_u32 s21, s26, 0xb00000
	v_readlane_b32 s5, v254, 60
	s_add_u32 s20, s4, s20
	s_addc_u32 s21, s5, s21
	v_readfirstlane_b32 s23, v0
	s_ashr_i32 s23, s23, 8
	s_add_i32 s23, s23, s22
	s_min_i32 s23, s23, 0x2bf
	s_mul_hi_i32 s27, s23, 0x2e8ba2e9
	s_lshr_b32 s28, s27, 31
	s_ashr_i32 s27, s27, 3
	s_add_i32 s27, s27, s28
	s_mul_i32 s28, s27, 44
	s_sub_i32 s23, s23, s28
	s_lshl_b32 s28, s27, 6
	v_bfe_u32 v6, v4, 6, 2
	s_ashr_i32 s29, s28, 31
	v_lshl_or_b32 v2, s23, 6, v6
	s_lshl_b64 s[28:29], s[28:29], 2
	s_add_u32 s28, s20, s28
	v_lshlrev_b32_e32 v0, 2, v4
	s_waitcnt vmcnt(15)
	v_or_b32_e32 v10, 4, v2
	s_waitcnt vmcnt(13)
	v_or_b32_e32 v12, 8, v2
	s_waitcnt vmcnt(12)
	v_or_b32_e32 v14, 12, v2
	s_waitcnt vmcnt(0)
	v_or_b32_e32 v16, 16, v2
	v_or_b32_e32 v22, 20, v2
	v_or_b32_e32 v24, 24, v2
	v_or_b32_e32 v26, 28, v2
	s_addc_u32 s29, s21, s29
	v_and_b32_e32 v0, 0xfc, v0
	v_ashrrev_i32_e32 v3, 31, v2
	v_ashrrev_i32_e32 v11, 31, v10
	v_ashrrev_i32_e32 v13, 31, v12
	v_ashrrev_i32_e32 v15, 31, v14
	v_ashrrev_i32_e32 v17, 31, v16
	s_waitcnt lgkmcnt(4)
	v_ashrrev_i32_e32 v23, 31, v22
	v_ashrrev_i32_e32 v25, 31, v24
	v_ashrrev_i32_e32 v27, 31, v26
	v_lshl_add_u64 v[20:21], s[28:29], 0, v[0:1]
	v_lshlrev_b64 v[8:9], 12, v[2:3]
	v_lshlrev_b64 v[10:11], 12, v[10:11]
	v_lshlrev_b64 v[12:13], 12, v[12:13]
	v_lshlrev_b64 v[14:15], 12, v[14:15]
	v_lshlrev_b64 v[16:17], 12, v[16:17]
	v_lshlrev_b64 v[22:23], 12, v[22:23]
	v_lshlrev_b64 v[24:25], 12, v[24:25]
	v_lshlrev_b64 v[26:27], 12, v[26:27]
	v_lshl_add_u64 v[8:9], v[20:21], 0, v[8:9]
	v_lshl_add_u64 v[10:11], v[20:21], 0, v[10:11]
	v_lshl_add_u64 v[12:13], v[20:21], 0, v[12:13]
	v_lshl_add_u64 v[14:15], v[20:21], 0, v[14:15]
	v_lshl_add_u64 v[16:17], v[20:21], 0, v[16:17]
	v_lshl_add_u64 v[22:23], v[20:21], 0, v[22:23]
	v_lshl_add_u64 v[24:25], v[20:21], 0, v[24:25]
	v_lshl_add_u64 v[26:27], v[20:21], 0, v[26:27]
	global_load_dword v8, v[8:9], off nt
	s_nop 0
	global_load_dword v9, v[10:11], off nt
	s_nop 0
	global_load_dword v11, v[12:13], off nt
	s_nop 0
	global_load_dword v13, v[14:15], off nt
	s_nop 0
	global_load_dword v14, v[16:17], off nt
	global_load_dword v15, v[22:23], off nt
	s_nop 0
	global_load_dword v16, v[24:25], off nt
	global_load_dword v17, v[26:27], off nt
	v_or_b32_e32 v22, 32, v2
	v_or_b32_e32 v24, 36, v2
	v_or_b32_e32 v26, 40, v2
	v_ashrrev_i32_e32 v23, 31, v22
	v_ashrrev_i32_e32 v25, 31, v24
	v_ashrrev_i32_e32 v27, 31, v26
	v_or_b32_e32 v28, 44, v2
	v_or_b32_e32 v30, 48, v2
	s_waitcnt lgkmcnt(0)
	v_or_b32_e32 v32, 52, v2
	v_or_b32_e32 v34, 56, v2
	v_or_b32_e32 v2, 60, v2
	v_lshlrev_b64 v[22:23], 12, v[22:23]
	v_lshlrev_b64 v[24:25], 12, v[24:25]
	v_lshlrev_b64 v[26:27], 12, v[26:27]
	v_ashrrev_i32_e32 v29, 31, v28
	v_ashrrev_i32_e32 v31, 31, v30
	v_ashrrev_i32_e32 v33, 31, v32
	v_ashrrev_i32_e32 v35, 31, v34
	v_ashrrev_i32_e32 v3, 31, v2
	v_lshl_add_u64 v[22:23], v[20:21], 0, v[22:23]
	v_lshl_add_u64 v[24:25], v[20:21], 0, v[24:25]
	v_lshl_add_u64 v[26:27], v[20:21], 0, v[26:27]
	v_lshlrev_b64 v[28:29], 12, v[28:29]
	v_lshlrev_b64 v[30:31], 12, v[30:31]
	v_lshlrev_b64 v[32:33], 12, v[32:33]
	v_lshlrev_b64 v[34:35], 12, v[34:35]
	v_lshlrev_b64 v[2:3], 12, v[2:3]
	v_lshl_add_u64 v[28:29], v[20:21], 0, v[28:29]
	v_lshl_add_u64 v[30:31], v[20:21], 0, v[30:31]
	v_lshl_add_u64 v[32:33], v[20:21], 0, v[32:33]
	v_lshl_add_u64 v[34:35], v[20:21], 0, v[34:35]
	v_lshl_add_u64 v[2:3], v[20:21], 0, v[2:3]
	global_load_dword v19, v[22:23], off nt
	global_load_dword v20, v[24:25], off nt
	global_load_dword v21, v[26:27], off nt
	s_nop 0
	global_load_dword v22, v[28:29], off nt
	global_load_dword v23, v[30:31], off nt
	global_load_dword v24, v[32:33], off nt
	global_load_dword v25, v[34:35], off nt
	global_load_dword v26, v[2:3], off nt
	v_bfe_u32 v7, v4, 3, 5
	v_lshlrev_b32_e32 v4, 3, v4
	v_and_b32_e32 v10, 56, v4
	v_mul_u32_u24_e32 v12, 0x41, v10
	v_lshlrev_b32_e32 v12, 2, v12
	v_lshlrev_b32_e32 v27, 2, v7
	v_lshlrev_b32_e32 v4, 1, v10
	v_mov_b32_e32 v5, v1
	v_add3_u32 v12, s33, v12, v27
	v_mul_u32_u24_e32 v27, 0x104, v6
	v_lshl_add_u64 v[2:3], s[20:21], 0, v[0:1]
	v_lshl_add_u64 v[4:5], s[0:1], 0, v[4:5]
	v_or_b32_e32 v10, 32, v7
	v_add3_u32 v0, s33, v27, v0
	v_readlane_b32 s6, v254, 61
	v_readlane_b32 s7, v254, 62
	v_readlane_b32 s8, v254, 63
	v_readlane_b32 s9, v255, 0
	v_readlane_b32 s10, v255, 1
	v_readlane_b32 s11, v255, 2
	v_readlane_b32 s12, v255, 3
	v_readlane_b32 s13, v255, 4
	v_readlane_b32 s14, v255, 5
	v_readlane_b32 s15, v255, 6
	v_readlane_b32 s16, v255, 7
	v_readlane_b32 s17, v255, 8
	v_readlane_b32 s18, v255, 9
	v_readlane_b32 s19, v255, 10
	s_waitcnt vmcnt(0)
	s_branch .LBB0_1071
